# attention: the top-of-step barrier (B1) removed - each wave now waits for its own K piece before the PV barrier (B5) of the previous step, so the K ring is already visible; 3 barriers per step instead
# speedup vs baseline: 1.0077x; 1.0077x over previous
; #define LAS __attribute__((address_space(3)))
; #define MFMA16(a, b, c) __builtin_amdgcn_mfma_f32_16x16x32_bf16((a), (b), (c), 0, 0, 0)
; #define SCHED_FENCE() __builtin_amdgcn_sched_barrier(0)
; __device__ __forceinline__ int att_fk(int key) { return ((key >> 3) & 3) + 4 * ((key >> 1) & 1); }
; #define ATT_K_PIECE(h_, row_, kg_) do { const int key = (kg_) * 8 + lr; \
;         __builtin_amdgcn_global_load_lds((const __attribute__((address_space(1))) unsigned*)(Kb + ((size_t)(row_) * 64 + key) * 1024 + (h_) * 64 + 8 * (lc ^ att_fk(key))), (LAS unsigned*)(KL + ((row_) & 7) * 8192 + (kg_) * 1024), 16, 0, 0); } while (0)
; #define ATT_BAR() do { asm volatile("s_waitcnt lgkmcnt(0)" ::: "memory"); __builtin_amdgcn_s_barrier(); asm volatile("" ::: "memory"); } while (0)
; __device__ __forceinline__ void attn_phase(const bf16_t* Q, const bf16_t* Kb, const bf16_t* VTa, const float* rpb, bf16_t* Y, LAS unsigned char* lds, int bx, int G, int tid, int wave, int lane) {
;     ...
;             float mx = -3.0e38f;
; #pragma unroll
;             for (int ii = 0; ii < 4; ++ii) {
;                 const int i = 4 * hf + ii, dr = rs + i - r + 7;
;                 float bia[8];
; #pragma unroll
;                 for (int j = 0; j < 8; ++j) bia[j] = rl[((unsigned)(j - wlo) < (unsigned)wwd) ? dr * 31 + dci0 + j : 480];
; #pragma unroll
;                 for (int ta = 0; ta < 2; ++ta) {
;                     const int key = cs + 8 * (fr >> 2) + 4 * ta + (fr & 3), fk = att_fk(key);
;                     const LAS unsigned char* kp = KL + ((rs + i) & 7) * 8192 + key * 128;
;                     const bf16x8 kf0 = *(const LAS bf16x8*)(kp + ((fq ^ fk) << 4)), kf1 = *(const LAS bf16x8*)(kp + (((4 + fq) ^ fk) << 4));
;                     f32x4 a = {0.f, 0.f, 0.f, 0.f};
;                     a = MFMA16(kf0, qf0, a); a = MFMA16(kf1, qf1, a);
; #pragma unroll
;                     for (int idx = 0; idx < 4; ++idx) { a[idx] += bia[4 * ta + idx]; mx = fmaxf(mx, a[idx]); }
;                     s[ii][ta] = a;
;                 }
;             }
;             ATT_BAR();
;             SCHED_FENCE();
;             if (newrow) ATT_K_PIECE(h, rs + 8, wave);
;             SCHED_FENCE();
;             if (has_next) { const bf16_t* qp = Q + (size_t)((r + 1) * 64 + c) * 1024 + h * 64 + 8 * fq; qf0 = *(const bf16x8*)qp; qf1 = *(const bf16x8*)(qp + 32); }
.Ltop1_d:
	v_lshl_add_u32 v190, v10, 2, s84
	v_cndmask_b32_e64 v11, v194, v190, s[40:41]
	v_add_u32_e32 v14, s75, v61
	s_waitcnt lgkmcnt(0)
	s_add_i32 s59, s64, s89
	s_add_i32 vcc_hi, s61, 0xffffff46
	s_lshl_b32 s59, s59, 13
	s_and_b32 vcc_lo, s59, 0xe000
	s_add_i32 s59, s64, s90
	s_addk_i32 s61, 0xff65
	s_lshl_b32 s59, s59, 13
	s_and_b32 s60, s59, 0xe000
	s_add_i32 s58, s30, s58
	s_add_i32 s31, s64, s91
	s_mul_i32 s59, s58, 31
	s_addk_i32 s59, 0xff27
	s_lshl_b32 s31, s31, 13
	s_and_b32 s58, s31, 0xe000
	v_add_u32_e32 v158, s75, v61
	v_add_u32_e32 v150, v158, v55
	v_add_u32_e32 v151, v158, v41
	v_add_u32_e32 v158, vcc_lo, v61
	v_add_u32_e32 v152, v158, v55
	v_add_u32_e32 v153, v158, v41
	v_add_u32_e32 v158, s60, v61
	v_add_u32_e32 v154, v158, v55
	v_add_u32_e32 v155, v158, v41
	v_add_u32_e32 v158, s58, v61
	v_add_u32_e32 v156, v158, v55
	v_add_u32_e32 v157, v158, v41
	v_add_u32_e32 v158, vcc_hi, v46
	v_lshl_add_u32 v191, v158, 2, s84
	v_add_u32_e32 v158, s61, v46
	v_lshl_add_u32 v192, v158, 2, s84
	v_add_u32_e32 v158, s59, v46
	v_lshl_add_u32 v193, v158, 2, s84
	ds_read_b128 v[118:121], v151
	ds_read_b128 v[122:125], v150
	ds_read_b128 v[126:129], v151 offset:512
	ds_read_b128 v[130:133], v150 offset:512
	ds_read_b128 v[134:137], v153
	ds_read_b128 v[138:141], v152
	ds_read_b128 v[142:145], v153 offset:512
	ds_read_b128 v[146:149], v152 offset:512
	s_waitcnt lgkmcnt(4)
	v_mfma_f32_16x16x32_bf16 v[10:13], v[118:121], v[6:9], 0
	v_mfma_f32_16x16x32_bf16 v[14:17], v[126:129], v[6:9], 0
	v_mfma_f32_16x16x32_bf16 v[10:13], v[122:125], v[2:5], v[10:13]
	v_mfma_f32_16x16x32_bf16 v[14:17], v[130:133], v[2:5], v[14:17]
	v_cndmask_b32_e64 v158, v194, v190, s[40:41]
	ds_read_b32 v202, v158
	v_cndmask_b32_e64 v159, v195, v190, s[42:43]
	ds_read_b32 v203, v159 offset:4
	v_cndmask_b32_e64 v158, v196, v190, s[44:45]
	ds_read_b32 v204, v158 offset:8
	v_cndmask_b32_e64 v159, v197, v190, s[46:47]
	ds_read_b32 v205, v159 offset:12
	v_cndmask_b32_e64 v158, v198, v190, s[48:49]
	ds_read_b32 v206, v158 offset:16
	v_cndmask_b32_e64 v159, v199, v190, s[50:51]
	ds_read_b32 v207, v159 offset:20
	v_cndmask_b32_e64 v158, v200, v190, s[52:53]
	ds_read_b32 v208, v158 offset:24
	v_cndmask_b32_e64 v159, v201, v190, s[54:55]
	ds_read_b32 v209, v159 offset:28
	ds_read_b128 v[118:121], v155
	ds_read_b128 v[122:125], v154
	ds_read_b128 v[126:129], v155 offset:512
	ds_read_b128 v[130:133], v154 offset:512
	s_waitcnt lgkmcnt(12)
	v_mfma_f32_16x16x32_bf16 v[18:21], v[134:137], v[6:9], 0
	v_mfma_f32_16x16x32_bf16 v[22:25], v[142:145], v[6:9], 0
	v_mfma_f32_16x16x32_bf16 v[18:21], v[138:141], v[2:5], v[18:21]
	v_mfma_f32_16x16x32_bf16 v[22:25], v[146:149], v[2:5], v[22:25]
	v_cndmask_b32_e64 v158, v194, v191, s[40:41]
	ds_read_b32 v210, v158
	v_cndmask_b32_e64 v159, v195, v191, s[42:43]
	ds_read_b32 v211, v159 offset:4
	v_cndmask_b32_e64 v158, v196, v191, s[44:45]
	ds_read_b32 v212, v158 offset:8
	v_cndmask_b32_e64 v159, v197, v191, s[46:47]
	ds_read_b32 v213, v159 offset:12
	v_cndmask_b32_e64 v158, v198, v191, s[48:49]
	ds_read_b32 v214, v158 offset:16
	v_cndmask_b32_e64 v159, v199, v191, s[50:51]
	ds_read_b32 v215, v159 offset:20
	v_cndmask_b32_e64 v158, v200, v191, s[52:53]
	ds_read_b32 v216, v158 offset:24
	v_cndmask_b32_e64 v159, v201, v191, s[54:55]
	ds_read_b32 v217, v159 offset:28
	ds_read_b128 v[134:137], v157
	ds_read_b128 v[138:141], v156
	ds_read_b128 v[142:145], v157 offset:512
	ds_read_b128 v[146:149], v156 offset:512
	s_waitcnt lgkmcnt(12)
	v_mfma_f32_16x16x32_bf16 v[26:29], v[118:121], v[6:9], 0
	v_mfma_f32_16x16x32_bf16 v[30:33], v[126:129], v[6:9], 0
	v_mfma_f32_16x16x32_bf16 v[26:29], v[122:125], v[2:5], v[26:29]
	v_mfma_f32_16x16x32_bf16 v[30:33], v[130:133], v[2:5], v[30:33]
	v_cndmask_b32_e64 v158, v194, v192, s[40:41]
	ds_read_b32 v102, v158
	v_cndmask_b32_e64 v159, v195, v192, s[42:43]
	ds_read_b32 v103, v159 offset:4
	v_cndmask_b32_e64 v158, v196, v192, s[44:45]
	ds_read_b32 v104, v158 offset:8
	v_cndmask_b32_e64 v159, v197, v192, s[46:47]
	ds_read_b32 v105, v159 offset:12
	v_cndmask_b32_e64 v158, v198, v192, s[48:49]
	ds_read_b32 v106, v158 offset:16
	v_cndmask_b32_e64 v159, v199, v192, s[50:51]
	ds_read_b32 v107, v159 offset:20
	v_cndmask_b32_e64 v158, v200, v192, s[52:53]
	ds_read_b32 v108, v158 offset:24
	v_cndmask_b32_e64 v159, v201, v192, s[54:55]
	ds_read_b32 v109, v159 offset:28
	s_waitcnt lgkmcnt(8)
	v_mfma_f32_16x16x32_bf16 v[34:37], v[134:137], v[6:9], 0
	v_mfma_f32_16x16x32_bf16 v[34:37], v[138:141], v[2:5], v[34:37]
	v_cndmask_b32_e64 v158, v194, v193, s[40:41]
	ds_read_b32 v110, v158
	v_cndmask_b32_e64 v159, v195, v193, s[42:43]
	ds_read_b32 v111, v159 offset:4
	v_cndmask_b32_e64 v158, v196, v193, s[44:45]
	ds_read_b32 v112, v158 offset:8
	v_cndmask_b32_e64 v159, v197, v193, s[46:47]
	ds_read_b32 v113, v159 offset:12
	v_cndmask_b32_e64 v158, v198, v193, s[48:49]
	ds_read_b32 v114, v158 offset:16
	v_cndmask_b32_e64 v159, v199, v193, s[50:51]
	ds_read_b32 v115, v159 offset:20
	v_cndmask_b32_e64 v158, v200, v193, s[52:53]
	ds_read_b32 v116, v158 offset:24
	v_cndmask_b32_e64 v159, v201, v193, s[54:55]
	ds_read_b32 v117, v159 offset:28
	s_cmp_eq_u32 s80, s64
	s_waitcnt lgkmcnt(0)
	s_barrier
	v_mfma_f32_16x16x32_bf16 v[6:9], v[142:145], v[6:9], 0
	v_mfma_f32_16x16x32_bf16 v[2:5], v[146:149], v[2:5], v[6:9]
	s_nop 0
	s_cbranch_scc1 .LBB0_453
	s_lshl_b32 s31, s64, 17
	s_add_u32 s58, s21, s31
	s_addc_u32 s59, s83, 0
	s_nop 1
	v_lshl_add_u64 v[6:7], s[58:59], 0, v[50:51]
	v_lshl_add_u64 v[6:7], v[6:7], 0, s[22:23]
	s_lshl_b32 s31, s64, 13
	v_lshl_add_u64 v[6:7], v[6:7], 0, v[0:1]
	s_mov_b64 s[58:59], 0x100000
	s_and_b32 s31, s31, 0xe000
	v_lshl_add_u64 v[6:7], v[6:7], 0, s[58:59]
	s_add_i32 m0, s86, s31
	s_nop 0
	global_load_lds_dwordx4 v[6:7], off

; #define ATT_V_PIECE(h_, row_, dg_) do { const int dh = (dg_) * 8 + lr; \
;         __builtin_amdgcn_global_load_lds((const __attribute__((address_space(1))) unsigned*)(VTa + (size_t)((h_) * 64 + dh) * T + (size_t)(row_) * 64 + 8 * (lc ^ att_fv(dh))), (LAS unsigned*)(VL + ((row_) & 7) * 8192 + (dg_) * 1024), 16, 0, 0); } while (0)
; #define ATT_BAR() do { asm volatile("s_waitcnt lgkmcnt(0)" ::: "memory"); __builtin_amdgcn_s_barrier(); asm volatile("" ::: "memory"); } while (0)
; __device__ __forceinline__ void attn_phase(const bf16_t* Q, const bf16_t* Kb, const bf16_t* VTa, const float* rpb, bf16_t* Y, LAS unsigned char* lds, int bx, int G, int tid, int wave, int lane) {
;     ...
;             if (newrow) asm volatile("s_waitcnt vmcnt(3)" ::: "memory"); else if (has_next) asm volatile("s_waitcnt vmcnt(2)" ::: "memory"); else asm volatile("s_waitcnt vmcnt(0)" ::: "memory");
;             ATT_BAR();
;     ...
;             if (newrow) ATT_V_PIECE(h, rs + 8, wave);
.LBB0_459:
	s_waitcnt vmcnt(2) lgkmcnt(0)
	s_barrier
	s_mov_b32 s32, 0
	s_and_b64 vcc, exec, s[60:61]
	s_cbranch_vccnz .Latt_novp
	s_lshl_b32 s31, s64, 13
	s_lshl_b32 s60, s64, 7
	s_mov_b32 s61, s23
	s_and_b32 s31, s31, 0xe000
	v_lshl_add_u64 v[228:229], v[96:97], 0, s[60:61]
	s_mov_b64 s[60:61], 0x400
	s_add_i32 m0, s88, s31
	v_lshl_add_u64 v[228:229], v[228:229], 0, s[60:61]
	global_load_lds_dwordx4 v[228:229], off
	s_mov_b32 s32, 1

; #define LAS __attribute__((address_space(3)))
; #define MFMA16(a, b, c) __builtin_amdgcn_mfma_f32_16x16x32_bf16((a), (b), (c), 0, 0, 0)
; __device__ __forceinline__ int att_fk(int key) { return ((key >> 3) & 3) + 4 * ((key >> 1) & 1); }
; #define ATT_BAR() do { asm volatile("s_waitcnt lgkmcnt(0)" ::: "memory"); __builtin_amdgcn_s_barrier(); asm volatile("" ::: "memory"); } while (0)
; __device__ __forceinline__ void attn_phase(const bf16_t* Q, const bf16_t* Kb, const bf16_t* VTa, const float* rpb, bf16_t* Y, LAS unsigned char* lds, int bx, int G, int tid, int wave, int lane) {
;     ...
;             float mx = -3.0e38f;
; #pragma unroll
;             for (int ii = 0; ii < 4; ++ii) {
;                 const int i = 4 * hf + ii, dr = rs + i - r + 7;
;                 float bia[8];
; #pragma unroll
;                 for (int j = 0; j < 8; ++j) bia[j] = rl[((unsigned)(j - wlo) < (unsigned)wwd) ? dr * 31 + dci0 + j : 480];
; #pragma unroll
;                 for (int ta = 0; ta < 2; ++ta) {
;                     const int key = cs + 8 * (fr >> 2) + 4 * ta + (fr & 3), fk = att_fk(key);
;                     const LAS unsigned char* kp = KL + ((rs + i) & 7) * 8192 + key * 128;
;                     const bf16x8 kf0 = *(const LAS bf16x8*)(kp + ((fq ^ fk) << 4)), kf1 = *(const LAS bf16x8*)(kp + (((4 + fq) ^ fk) << 4));
;                     f32x4 a = {0.f, 0.f, 0.f, 0.f};
;                     a = MFMA16(kf0, qf0, a); a = MFMA16(kf1, qf1, a);
; #pragma unroll
;                     for (int idx = 0; idx < 4; ++idx) { a[idx] += bia[4 * ta + idx]; mx = fmaxf(mx, a[idx]); }
;                     s[ii][ta] = a;
;                 }
;             }
;             ATT_BAR();
.Ltop0_d:
	v_lshl_add_u32 v190, v10, 2, s84
	v_cndmask_b32_e64 v11, v194, v190, s[40:41]
	v_add_u32_e32 v14, s31, v61
	s_waitcnt lgkmcnt(0)
	v_add_u32_e32 v27, v14, v55
	ds_read_b32 v18, v11
	v_add_u32_e32 v26, v14, v41
	ds_read_b128 v[14:17], v27
	v_cndmask_b32_e64 v11, v195, v190, s[42:43]
	ds_read_b32 v19, v11 offset:4
	v_cndmask_b32_e64 v11, v196, v190, s[44:45]
	ds_read_b32 v20, v11 offset:8
	v_cndmask_b32_e64 v11, v197, v190, s[46:47]
	ds_read_b32 v21, v11 offset:12
	v_cndmask_b32_e64 v11, v198, v190, s[48:49]
	ds_read_b32 v22, v11 offset:16
	v_cndmask_b32_e64 v11, v199, v190, s[50:51]
	ds_read_b32 v23, v11 offset:20
	v_cndmask_b32_e64 v11, v200, v190, s[52:53]
	v_cndmask_b32_e64 v10, v201, v190, s[54:55]
	ds_read_b32 v24, v11 offset:24
	ds_read_b32 v25, v10 offset:28
	ds_read_b128 v[10:13], v26
	s_waitcnt lgkmcnt(0)
	v_mfma_f32_16x16x32_bf16 v[10:13], v[10:13], v[6:9], 0
	s_add_i32 s31, s30, s89
	s_sub_i32 s60, s31, s20
	s_lshl_b32 s31, s31, 13
	v_mfma_f32_16x16x32_bf16 v[14:17], v[14:17], v[2:5], v[10:13]
	s_and_b32 s31, s31, 0xe000
	s_nop 6
	v_add_f32_e32 v13, v18, v14
	v_add_f32_e32 v12, v19, v15
	v_max3_f32 v14, v13, s6, v12
	v_add_f32_e32 v11, v20, v16
	v_add_f32_e32 v10, v21, v17
	v_max3_f32 v28, v14, v11, v10
	ds_read_b128 v[14:17], v26 offset:512
	ds_read_b128 v[18:21], v27 offset:512
	s_waitcnt lgkmcnt(1)
	v_mfma_f32_16x16x32_bf16 v[14:17], v[14:17], v[6:9], 0
	s_waitcnt lgkmcnt(0)
	v_mfma_f32_16x16x32_bf16 v[18:21], v[18:21], v[2:5], v[14:17]
	s_nop 7
	v_add_f32_e32 v17, v22, v18
	v_add_f32_e32 v16, v23, v19
	v_max3_f32 v18, v28, v17, v16
	v_add_f32_e32 v15, v24, v20
	v_add_f32_e32 v14, v25, v21
	v_max3_f32 v26, v18, v15, v14
	v_mad_u64_u32 v[18:19], s[60:61], s60, 31, v[46:47]
	v_lshl_add_u32 v191, v18, 2, s84
	v_cndmask_b32_e64 v19, v194, v191, s[40:41]
	v_add_u32_e32 v22, s31, v61
	v_add_u32_e32 v63, v22, v55
	ds_read_b32 v27, v19
	v_add_u32_e32 v37, v22, v41
	ds_read_b128 v[22:25], v63
	v_cndmask_b32_e64 v19, v195, v191, s[42:43]
	ds_read_b32 v28, v19 offset:4
	v_cndmask_b32_e64 v19, v196, v191, s[44:45]
	ds_read_b32 v29, v19 offset:8
	v_cndmask_b32_e64 v19, v197, v191, s[46:47]
	ds_read_b32 v30, v19 offset:12
	v_cndmask_b32_e64 v19, v198, v191, s[48:49]
	ds_read_b32 v32, v19 offset:16
	v_cndmask_b32_e64 v19, v199, v191, s[50:51]
	ds_read_b32 v33, v19 offset:20
	v_cndmask_b32_e64 v19, v200, v191, s[52:53]
	v_cndmask_b32_e64 v18, v201, v191, s[54:55]
	ds_read_b32 v35, v19 offset:24
	ds_read_b32 v36, v18 offset:28
	ds_read_b128 v[18:21], v37
	s_waitcnt lgkmcnt(0)
	v_mfma_f32_16x16x32_bf16 v[18:21], v[18:21], v[6:9], 0
	s_add_i32 s31, s30, s90
	s_sub_i32 s60, s31, s20
	s_lshl_b32 s31, s31, 13
	v_mfma_f32_16x16x32_bf16 v[22:25], v[22:25], v[2:5], v[18:21]
	s_and_b32 s31, s31, 0xe000
	v_add_u32_e32 v73, s31, v61
	v_add_u32_e32 v75, v73, v41
	v_add_u32_e32 v73, v73, v55
	s_add_i32 s31, s30, s91
	s_nop 2
	v_add_f32_e32 v22, v27, v22
	v_add_f32_e32 v21, v28, v23
	v_max3_f32 v18, v26, v22, v21
	v_add_f32_e32 v20, v29, v24
	v_add_f32_e32 v19, v30, v25
	ds_read_b128 v[24:27], v37 offset:512
	ds_read_b128 v[92:95], v63 offset:512
	s_waitcnt lgkmcnt(1)
	v_mfma_f32_16x16x32_bf16 v[24:27], v[24:27], v[6:9], 0
	v_max3_f32 v18, v18, v20, v19
	s_waitcnt lgkmcnt(0)
	v_mfma_f32_16x16x32_bf16 v[24:27], v[92:95], v[2:5], v[24:27]
	ds_read_b128 v[92:95], v73
	s_nop 6
	v_add_f32_e32 v23, v32, v24
	v_add_f32_e32 v28, v33, v25
	v_mad_u64_u32 v[24:25], s[60:61], s60, 31, v[46:47]
	v_lshl_add_u32 v192, v24, 2, s84
	v_cndmask_b32_e64 v25, v194, v192, s[40:41]
	ds_read_b32 v32, v25
	v_cndmask_b32_e64 v25, v195, v192, s[42:43]
	ds_read_b32 v33, v25 offset:4
	v_cndmask_b32_e64 v25, v196, v192, s[44:45]
	v_add_f32_e32 v29, v35, v26
	ds_read_b32 v35, v25 offset:8
	v_cndmask_b32_e64 v25, v197, v192, s[46:47]
	v_add_f32_e32 v30, v36, v27
	ds_read_b32 v36, v25 offset:12
	v_cndmask_b32_e64 v25, v198, v192, s[48:49]
	ds_read_b32 v37, v25 offset:16
	v_cndmask_b32_e64 v25, v199, v192, s[50:51]
	ds_read_b32 v63, v25 offset:20
	v_cndmask_b32_e64 v25, v200, v192, s[52:53]
	v_cndmask_b32_e64 v24, v201, v192, s[54:55]
	ds_read_b32 v65, v25 offset:24
	ds_read_b32 v71, v24 offset:28
	ds_read_b128 v[24:27], v75
	s_waitcnt lgkmcnt(0)
	v_mfma_f32_16x16x32_bf16 v[24:27], v[24:27], v[6:9], 0
	s_sub_i32 s60, s31, s20
	s_lshl_b32 s31, s31, 13
	s_and_b32 s31, s31, 0xe000
	v_mfma_f32_16x16x32_bf16 v[24:27], v[92:95], v[2:5], v[24:27]
	v_add_u32_e32 v89, s31, v61
	v_add_u32_e32 v91, v89, v41
	v_add_u32_e32 v89, v89, v55
	v_max3_f32 v18, v18, v23, v28
	v_max3_f32 v18, v18, v29, v30
	s_nop 2
	v_add_f32_e32 v32, v32, v24
	v_add_f32_e32 v33, v33, v25
	v_add_f32_e32 v35, v35, v26
	v_add_f32_e32 v36, v36, v27
	ds_read_b128 v[24:27], v75 offset:512
	ds_read_b128 v[92:95], v73 offset:512
	s_waitcnt lgkmcnt(1)
	v_mfma_f32_16x16x32_bf16 v[24:27], v[24:27], v[6:9], 0
	v_max3_f32 v18, v18, v32, v33
	v_max3_f32 v18, v18, v35, v36
	s_waitcnt lgkmcnt(0)
	v_mfma_f32_16x16x32_bf16 v[24:27], v[92:95], v[2:5], v[24:27]
	ds_read_b128 v[92:95], v89
	s_nop 6
	v_add_f32_e32 v37, v37, v24
	v_add_f32_e32 v63, v63, v25
	v_mad_u64_u32 v[24:25], s[60:61], s60, 31, v[46:47]
	v_lshl_add_u32 v193, v24, 2, s84
	v_cndmask_b32_e64 v25, v194, v193, s[40:41]
	ds_read_b32 v73, v25
	v_cndmask_b32_e64 v25, v195, v193, s[42:43]
	ds_read_b32 v75, v25 offset:4
	v_cndmask_b32_e64 v25, v196, v193, s[44:45]
	ds_read_b32 v77, v25 offset:8
	v_cndmask_b32_e64 v25, v197, v193, s[46:47]
	ds_read_b32 v79, v25 offset:12
	v_cndmask_b32_e64 v25, v198, v193, s[48:49]
	ds_read_b32 v81, v25 offset:16
	v_cndmask_b32_e64 v25, v199, v193, s[50:51]
	ds_read_b32 v83, v25 offset:20
	v_cndmask_b32_e64 v25, v200, v193, s[52:53]
	v_cndmask_b32_e64 v24, v201, v193, s[54:55]
	v_add_f32_e32 v65, v65, v26
	v_add_f32_e32 v71, v71, v27
	ds_read_b32 v85, v25 offset:24
	ds_read_b32 v87, v24 offset:28
	ds_read_b128 v[24:27], v91
	s_waitcnt lgkmcnt(0)
	v_mfma_f32_16x16x32_bf16 v[24:27], v[24:27], v[6:9], 0
	v_max3_f32 v18, v18, v37, v63
	v_max3_f32 v18, v18, v65, v71
	v_mfma_f32_16x16x32_bf16 v[24:27], v[92:95], v[2:5], v[24:27]
	s_nop 7
	v_add_f32_e32 v73, v73, v24
	v_add_f32_e32 v75, v75, v25
	v_add_f32_e32 v77, v77, v26
	v_add_f32_e32 v79, v79, v27
	ds_read_b128 v[24:27], v91 offset:512
	ds_read_b128 v[92:95], v89 offset:512
	s_waitcnt lgkmcnt(1)
	v_mfma_f32_16x16x32_bf16 v[6:9], v[24:27], v[6:9], 0
	v_max3_f32 v18, v18, v73, v75
	v_max3_f32 v18, v18, v77, v79
	s_waitcnt lgkmcnt(0)
	s_waitcnt lgkmcnt(0)
	v_mfma_f32_16x16x32_bf16 v[2:5], v[92:95], v[2:5], v[6:9]
	s_barrier
; __device__ __forceinline__ float fast_exp2(float x) { return __builtin_amdgcn_exp2f(x); }
; __device__ __forceinline__ u32x4 pack8(f32x4 a, f32x4 b) { u32x4 w; w.x = cvt_pk_bf16(a[0], a[1]); w.y = cvt_pk_bf16(a[2], a[3]); w.z = cvt_pk_bf16(b[0], b[1]); w.w = cvt_pk_bf16(b[2], b[3]); return w; }
; #define SCHED_FENCE() __builtin_amdgcn_sched_barrier(0)
; #define ATT_BAR() do { asm volatile("s_waitcnt lgkmcnt(0)" ::: "memory"); __builtin_amdgcn_s_barrier(); asm volatile("" ::: "memory"); } while (0)
; __device__ __forceinline__ void attn_phase(const bf16_t* Q, const bf16_t* Kb, const bf16_t* VTa, const float* rpb, bf16_t* Y, LAS unsigned char* lds, int bx, int G, int tid, int wave, int lane) {
;     ...
;             mx = fmaxf(mx, __shfl_xor(mx, 16)); mx = fmaxf(mx, __shfl_xor(mx, 32));
;             float l = 0.f;
;             bf16x8 pb[4];
; #pragma unroll
;             for (int ii = 0; ii < 4; ++ii) {
;                 f32x4 p0, p1;
; #pragma unroll
;                 for (int idx = 0; idx < 4; ++idx) { p0[idx] = fast_exp2((s[ii][0][idx] - mx) * 1.4426950409f); p1[idx] = fast_exp2((s[ii][1][idx] - mx) * 1.4426950409f); }
;                 l += (p0[0] + p0[1]) + (p0[2] + p0[3]) + (p1[0] + p1[1]) + (p1[2] + p1[3]);
;                 const u32x4 pw = pack8(p0, p1); pb[ii] = __builtin_bit_cast(bf16x8, pw);
;             }
;             l += __shfl_xor(l, 16); l += __shfl_xor(l, 32);
;             SCHED_FENCE();
;             if (newrow) asm volatile("s_waitcnt vmcnt(3)" ::: "memory"); else if (has_next) asm volatile("s_waitcnt vmcnt(2)" ::: "memory"); else asm volatile("s_waitcnt vmcnt(0)" ::: "memory");
;             ATT_BAR();
	s_nop 6
	v_add_f32_e32 v24, v81, v2
	v_add_f32_e32 v25, v83, v3
	v_max3_f32 v2, v18, v24, v25
	v_add_f32_e32 v26, v85, v4
	v_add_f32_e32 v27, v87, v5
	v_max3_f32 v2, v2, v26, v27
	ds_bpermute_b32 v3, v31, v2
	s_waitcnt lgkmcnt(0)
	v_max_f32_e32 v3, v3, v3
	v_max_f32_e32 v2, v2, v3
	ds_bpermute_b32 v3, v34, v2
	s_waitcnt lgkmcnt(0)
	v_max_f32_e32 v3, v3, v3
	v_max_f32_e32 v18, v2, v3
	v_sub_f32_e32 v3, v17, v18
	v_sub_f32_e32 v4, v12, v18
	v_sub_f32_e32 v5, v16, v18
	v_mul_f32_e32 v3, 0x3fb8aa3b, v3
	v_mul_f32_e32 v4, 0x3fb8aa3b, v4
	v_mul_f32_e32 v5, 0x3fb8aa3b, v5
	v_sub_f32_e32 v2, v13, v18
	v_exp_f32_e32 v6, v3
	v_exp_f32_e32 v3, v4
	v_exp_f32_e32 v4, v5
	v_sub_f32_e32 v5, v11, v18
	v_sub_f32_e32 v8, v10, v18
	v_mul_f32_e32 v2, 0x3fb8aa3b, v2
	v_mul_f32_e32 v5, 0x3fb8aa3b, v5
	v_mul_f32_e32 v8, 0x3fb8aa3b, v8
	v_exp_f32_e32 v2, v2
	v_exp_f32_e32 v5, v5
	v_sub_f32_e32 v7, v15, v18
	v_exp_f32_e32 v8, v8
	v_sub_f32_e32 v9, v14, v18
	v_mul_f32_e32 v7, 0x3fb8aa3b, v7
	v_mul_f32_e32 v9, 0x3fb8aa3b, v9
	v_exp_f32_e32 v7, v7
	v_exp_f32_e32 v9, v9
	v_add_f32_e32 v10, v2, v3
	v_add_f32_e32 v11, v5, v8
	v_add_f32_e32 v10, v10, v11
	v_add_f32_e32 v11, v6, v4
	v_add_f32_e32 v10, v11, v10
	v_add_f32_e32 v11, v7, v9
	v_cvt_pk_bf16_f32 v2, v2, v3
	v_cvt_pk_bf16_f32 v3, v5, v8
	v_cvt_pk_bf16_f32 v4, v6, v4
	v_cvt_pk_bf16_f32 v5, v7, v9
	v_sub_f32_e32 v7, v23, v18
	v_mul_f32_e32 v7, 0x3fb8aa3b, v7
	v_add_f32_e32 v10, v11, v10
	v_sub_f32_e32 v6, v22, v18
	v_exp_f32_e32 v8, v7
	v_sub_f32_e32 v7, v21, v18
	v_sub_f32_e32 v11, v20, v18
	v_sub_f32_e32 v13, v19, v18
	v_mul_f32_e32 v6, 0x3fb8aa3b, v6
	v_mul_f32_e32 v7, 0x3fb8aa3b, v7
	v_sub_f32_e32 v9, v28, v18
	v_mul_f32_e32 v11, 0x3fb8aa3b, v11
	v_mul_f32_e32 v13, 0x3fb8aa3b, v13
	v_exp_f32_e32 v6, v6
	v_exp_f32_e32 v7, v7
	v_mul_f32_e32 v9, 0x3fb8aa3b, v9
	v_exp_f32_e32 v11, v11
	v_sub_f32_e32 v12, v29, v18
	v_exp_f32_e32 v13, v13
	v_sub_f32_e32 v14, v30, v18
	v_exp_f32_e32 v9, v9
	v_mul_f32_e32 v12, 0x3fb8aa3b, v12
	v_mul_f32_e32 v14, 0x3fb8aa3b, v14
	v_exp_f32_e32 v12, v12
	v_exp_f32_e32 v14, v14
	v_add_f32_e32 v15, v6, v7
	v_add_f32_e32 v16, v11, v13
	v_add_f32_e32 v15, v15, v16
	v_add_f32_e32 v16, v8, v9
	v_add_f32_e32 v15, v16, v15
	v_add_f32_e32 v16, v12, v14
	v_add_f32_e32 v10, 0, v10
	v_add_f32_e32 v15, v16, v15
	v_add_f32_e32 v10, v15, v10
	v_cvt_pk_bf16_f32 v6, v6, v7
	v_cvt_pk_bf16_f32 v7, v11, v13
	v_sub_f32_e32 v11, v32, v18
	v_sub_f32_e32 v13, v33, v18
	v_sub_f32_e32 v15, v35, v18
	v_sub_f32_e32 v17, v36, v18
	v_cvt_pk_bf16_f32 v8, v8, v9
	v_cvt_pk_bf16_f32 v9, v12, v14
	v_mul_f32_e32 v11, 0x3fb8aa3b, v11
	v_sub_f32_e32 v12, v37, v18
	v_mul_f32_e32 v13, 0x3fb8aa3b, v13
	v_sub_f32_e32 v14, v63, v18
	v_mul_f32_e32 v15, 0x3fb8aa3b, v15
	v_mul_f32_e32 v17, 0x3fb8aa3b, v17
	v_exp_f32_e32 v11, v11
	v_mul_f32_e32 v12, 0x3fb8aa3b, v12
	v_exp_f32_e32 v13, v13
	v_mul_f32_e32 v14, 0x3fb8aa3b, v14
	v_exp_f32_e32 v15, v15
	v_sub_f32_e32 v16, v65, v18
	v_exp_f32_e32 v17, v17
	v_sub_f32_e32 v19, v71, v18
	v_exp_f32_e32 v12, v12
	v_exp_f32_e32 v14, v14
	v_mul_f32_e32 v16, 0x3fb8aa3b, v16
	v_mul_f32_e32 v19, 0x3fb8aa3b, v19
	v_exp_f32_e32 v16, v16
	v_exp_f32_e32 v19, v19
	v_add_f32_e32 v20, v11, v13
	v_add_f32_e32 v21, v15, v17
	v_add_f32_e32 v20, v20, v21
	v_add_f32_e32 v21, v12, v14
	v_add_f32_e32 v20, v21, v20
	v_add_f32_e32 v21, v16, v19
	v_add_f32_e32 v20, v21, v20
	v_sub_f32_e32 v21, v24, v18
	v_mul_f32_e32 v21, 0x3fb8aa3b, v21
	v_add_f32_e32 v10, v20, v10
	v_sub_f32_e32 v20, v73, v18
	v_exp_f32_e32 v22, v21
	v_sub_f32_e32 v21, v75, v18
	v_sub_f32_e32 v23, v25, v18
	v_sub_f32_e32 v24, v77, v18
	v_sub_f32_e32 v25, v26, v18
	v_sub_f32_e32 v26, v79, v18
	v_mul_f32_e32 v20, 0x3fb8aa3b, v20
	v_mul_f32_e32 v21, 0x3fb8aa3b, v21
	v_mul_f32_e32 v24, 0x3fb8aa3b, v24
	v_mul_f32_e32 v26, 0x3fb8aa3b, v26
	v_exp_f32_e32 v20, v20
	v_exp_f32_e32 v21, v21
	v_mul_f32_e32 v23, 0x3fb8aa3b, v23
	v_exp_f32_e32 v24, v24
	v_exp_f32_e32 v26, v26
	v_sub_f32_e32 v27, v27, v18
	v_exp_f32_e32 v23, v23
	v_mul_f32_e32 v25, 0x3fb8aa3b, v25
	v_mul_f32_e32 v27, 0x3fb8aa3b, v27
	v_exp_f32_e32 v25, v25
	v_exp_f32_e32 v27, v27
	v_add_f32_e32 v28, v20, v21
	v_add_f32_e32 v29, v24, v26
	v_add_f32_e32 v28, v28, v29
	v_add_f32_e32 v29, v22, v23
	v_add_f32_e32 v28, v29, v28
	v_add_f32_e32 v29, v25, v27
	v_add_f32_e32 v28, v29, v28
	v_add_f32_e32 v28, v28, v10
	ds_bpermute_b32 v29, v31, v28
	v_cvt_pk_bf16_f32 v10, v11, v13
	v_cvt_pk_bf16_f32 v11, v15, v17
	v_cvt_pk_bf16_f32 v12, v12, v14
	v_cvt_pk_bf16_f32 v13, v16, v19
	s_waitcnt lgkmcnt(0)
	v_add_f32_e32 v14, v28, v29
	ds_bpermute_b32 v15, v34, v14
	v_cvt_pk_bf16_f32 v20, v20, v21
	v_cvt_pk_bf16_f32 v21, v24, v26
	v_cvt_pk_bf16_f32 v22, v22, v23
	v_cvt_pk_bf16_f32 v23, v25, v27
	s_waitcnt lgkmcnt(0)
	v_add_f32_e32 v19, v14, v15
	s_or_b32 s30, s30, s87
	s_lshl_b32 s30, s30, 13
	s_waitcnt vmcnt(0)
	s_and_b32 s31, s30, 0xe000
	s_waitcnt lgkmcnt(0)
	s_barrier
; #define LAS __attribute__((address_space(3)))
; __device__ __forceinline__ unsigned cvt_pk_bf16(float lo, float hi) { unsigned r; asm volatile("v_cvt_pk_bf16_f32 %0, %1, %2" : "=v"(r) : "v"(lo), "v"(hi)); return r; }
; #define MFMA16(a, b, c) __builtin_amdgcn_mfma_f32_16x16x32_bf16((a), (b), (c), 0, 0, 0)
; __device__ __forceinline__ int att_fv(int dh) { return (dh >> 1) & 7; }
; __device__ __forceinline__ void attn_phase(const bf16_t* Q, const bf16_t* Kb, const bf16_t* VTa, const float* rpb, bf16_t* Y, LAS unsigned char* lds, int bx, int G, int tid, int wave, int lane) {
;     ...
;             f32x4 o[4];
; #pragma unroll
;             for (int dt = 0; dt < 4; ++dt) o[dt] = (f32x4){0.f, 0.f, 0.f, 0.f};
; #pragma unroll
;             for (int ii = 0; ii < 4; ++ii) {
;                 const int i = 4 * hf + ii;
; #pragma unroll
;                 for (int dt = 0; dt < 4; ++dt) { const int dh = 16 * dt + fr;
;                     const bf16x8 vf = *(const LAS bf16x8*)(VL + ((rs + i) & 7) * 8192 + dh * 128 + ((((cs >> 3) + fq) ^ att_fv(dh)) << 4));
;                     o[dt] = MFMA16(vf, pb[ii], o[dt]); }
;             }
;             LAS float* ml = (LAS float*)(lds + 131072 + 2048) + (size_t)(g * 64 + lane) * 2;
;             LAS u32x2* ol = (LAS u32x2*)(lds + 131072 + 4096) + (size_t)(g * 64 + lane) * 4;
;             if (hf == 1) {
; #pragma unroll
;                 for (int dt = 0; dt < 4; ++dt) { u32x2 w; w.x = cvt_pk_bf16(o[dt][0], o[dt][1]); w.y = cvt_pk_bf16(o[dt][2], o[dt][3]); ol[dt] = w; }
;                 ml[0] = mx; ml[1] = l;
;             }
	v_add_u32_e32 v32, s31, v49
	s_add_i32 s31, s30, 0x2000
	s_and_b32 s31, s31, 0xe000
	v_add_u32_e32 v33, s31, v49
	s_add_i32 s31, s30, 0x4000
	s_and_b32 s31, s31, 0xe000
	v_add_u32_e32 v34, s31, v49
	s_addk_i32 s30, 0x6000
	s_and_b32 s30, s30, 0xe000
	v_add_u32_e32 v35, s30, v49
	s_and_b64 vcc, exec, s[58:59]
	ds_read_b128 v[108:111], v32
	ds_read_b128 v[112:115], v32 offset:2048
	ds_read_b128 v[116:119], v32 offset:4096
	ds_read_b128 v[120:123], v32 offset:6144
	ds_read_b128 v[124:127], v33
	ds_read_b128 v[128:131], v33 offset:2048
	ds_read_b128 v[132:135], v33 offset:4096
	ds_read_b128 v[136:139], v33 offset:6144
	ds_read_b128 v[140:143], v34
	ds_read_b128 v[144:147], v34 offset:2048
	ds_read_b128 v[148:151], v34 offset:4096
	ds_read_b128 v[152:155], v34 offset:6144
	ds_read_b128 v[174:177], v35
	ds_read_b128 v[178:181], v35 offset:2048
	ds_read_b128 v[182:185], v35 offset:4096
	ds_read_b128 v[186:189], v35 offset:6144
	s_waitcnt lgkmcnt(12)
	v_mfma_f32_16x16x32_bf16 v[14:17], v[108:111], v[2:5], 0
	v_mfma_f32_16x16x32_bf16 v[24:27], v[112:115], v[2:5], 0
	v_mfma_f32_16x16x32_bf16 v[28:31], v[116:119], v[2:5], 0
	v_mfma_f32_16x16x32_bf16 v[2:5], v[120:123], v[2:5], 0
	s_waitcnt lgkmcnt(8)
	v_mfma_f32_16x16x32_bf16 v[14:17], v[124:127], v[6:9], v[14:17]
	v_mfma_f32_16x16x32_bf16 v[24:27], v[128:131], v[6:9], v[24:27]
	v_mfma_f32_16x16x32_bf16 v[28:31], v[132:135], v[6:9], v[28:31]
	v_mfma_f32_16x16x32_bf16 v[2:5], v[136:139], v[6:9], v[2:5]
	s_waitcnt lgkmcnt(4)
	v_mfma_f32_16x16x32_bf16 v[14:17], v[140:143], v[10:13], v[14:17]
	v_mfma_f32_16x16x32_bf16 v[24:27], v[144:147], v[10:13], v[24:27]
	v_mfma_f32_16x16x32_bf16 v[28:31], v[148:151], v[10:13], v[28:31]
	v_mfma_f32_16x16x32_bf16 v[2:5], v[152:155], v[10:13], v[2:5]
	s_waitcnt lgkmcnt(0)
	v_mfma_f32_16x16x32_bf16 v[14:17], v[174:177], v[20:23], v[14:17]
	v_mfma_f32_16x16x32_bf16 v[10:13], v[178:181], v[20:23], v[24:27]
	v_mfma_f32_16x16x32_bf16 v[6:9], v[182:185], v[20:23], v[28:31]
	v_mfma_f32_16x16x32_bf16 v[2:5], v[186:189], v[20:23], v[2:5]
	s_nop 7
	v_add_u32_e32 v20, 0, v59
	v_add_u32_e32 v21, 0, v57
	v_add_u32_e32 v20, 0x21000, v20
	v_add_u32_e32 v21, 0x20800, v21
	s_cbranch_vccnz .LBB0_467
	v_cvt_pk_bf16_f32 v22, v14, v15
	v_cvt_pk_bf16_f32 v23, v16, v17
	ds_write_b64 v20, v[22:23]
	v_cvt_pk_bf16_f32 v22, v10, v11
	v_cvt_pk_bf16_f32 v23, v12, v13
	ds_write_b64 v20, v[22:23] offset:8
	v_cvt_pk_bf16_f32 v22, v6, v7
	v_cvt_pk_bf16_f32 v23, v8, v9
	ds_write_b64 v20, v[22:23] offset:16
	v_cvt_pk_bf16_f32 v22, v2, v3
	v_cvt_pk_bf16_f32 v23, v4, v5
	ds_write_b64 v20, v[22:23] offset:24
	ds_write_b64 v21, v[18:19]
